# grid barrier: workgroups that are not their XCD's leader poll the cross-XCD generation word directly instead of waiting for a second per-XCD release hop
# speedup vs baseline: 1.0005x; 1.0005x over previous
.LBB0_672:
	s_or_b64 exec, exec, s[36:37]
	v_cvt_f32_u32_e32 v5, v3
	s_waitcnt vmcnt(0)
	v_readfirstlane_b32 s20, v4
	v_sub_u32_e32 v4, 0, v3
	v_rcp_iflag_f32_e32 v5, v5
	v_add_u32_e32 v6, s20, v0
	v_mul_f32_e32 v5, 0x4f7ffffe, v5
	v_cvt_u32_f32_e32 v5, v5
	v_mul_lo_u32 v0, v4, v5
	v_mul_hi_u32 v0, v5, v0
	v_add_u32_e32 v0, v5, v0
	v_mul_hi_u32 v0, v6, v0
	v_mul_lo_u32 v4, v0, v3
	v_sub_u32_e32 v4, v6, v4
	v_add_u32_e32 v5, 1, v0
	v_cmp_ge_u32_e32 vcc, v4, v3
	s_nop 1
	v_cndmask_b32_e32 v0, v0, v5, vcc
	v_sub_u32_e32 v5, v4, v3
	v_cndmask_b32_e32 v4, v4, v5, vcc
	v_add_u32_e32 v5, 1, v0
	v_cmp_ge_u32_e32 vcc, v4, v3
	v_add_u32_e32 v4, 1, v6
	s_nop 0
	v_cndmask_b32_e32 v0, v0, v5, vcc
	v_mul_lo_u32 v5, v3, v0
	v_add_u32_e32 v3, v5, v3
	v_cmp_ne_u32_e32 vcc, v4, v3
	s_and_saveexec_b64 s[20:21], vcc
	s_xor_b64 s[36:37], exec, s[20:21]
	s_cbranch_execz .LBB0_686
	v_readlane_b32 s12, v254, 50
	v_readlane_b32 s13, v254, 51
	s_waitcnt lgkmcnt(0)
	s_nop 3
	global_load_dword v2, v1, s[12:13] sc1
	s_waitcnt vmcnt(0)
	v_cmp_eq_u32_e32 vcc, v2, v0
	s_and_saveexec_b64 s[38:39], vcc
	s_cbranch_execz .LBB0_685
	s_mov_b32 s20, 1
	s_mov_b64 s[42:43], 0
	s_branch .LBB0_676

.LBB0_1114:
	s_or_b64 exec, exec, s[36:37]
	v_cvt_f32_u32_e32 v5, v3
	s_waitcnt vmcnt(0)
	v_readfirstlane_b32 s19, v4
	v_sub_u32_e32 v4, 0, v3
	v_rcp_iflag_f32_e32 v5, v5
	v_add_u32_e32 v6, s19, v0
	v_mul_f32_e32 v5, 0x4f7ffffe, v5
	v_cvt_u32_f32_e32 v5, v5
	v_mul_lo_u32 v0, v4, v5
	v_mul_hi_u32 v0, v5, v0
	v_add_u32_e32 v0, v5, v0
	v_mul_hi_u32 v0, v6, v0
	v_mul_lo_u32 v4, v0, v3
	v_sub_u32_e32 v4, v6, v4
	v_add_u32_e32 v5, 1, v0
	v_cmp_ge_u32_e32 vcc, v4, v3
	s_nop 1
	v_cndmask_b32_e32 v0, v0, v5, vcc
	v_sub_u32_e32 v5, v4, v3
	v_cndmask_b32_e32 v4, v4, v5, vcc
	v_add_u32_e32 v5, 1, v0
	v_cmp_ge_u32_e32 vcc, v4, v3
	v_add_u32_e32 v4, 1, v6
	s_nop 0
	v_cndmask_b32_e32 v0, v0, v5, vcc
	v_mul_lo_u32 v5, v3, v0
	v_add_u32_e32 v3, v5, v3
	v_cmp_ne_u32_e32 vcc, v4, v3
	s_and_saveexec_b64 s[20:21], vcc
	s_xor_b64 s[36:37], exec, s[20:21]
	s_cbranch_execz .LBB0_1128
	v_readlane_b32 s12, v254, 50
	v_readlane_b32 s13, v254, 51
	s_waitcnt lgkmcnt(0)
	s_nop 3
	global_load_dword v2, v1, s[12:13] sc1
	s_waitcnt vmcnt(0)
	v_cmp_eq_u32_e32 vcc, v2, v0
	s_and_saveexec_b64 s[38:39], vcc
	s_cbranch_execz .LBB0_1127
	s_mov_b32 s19, 1
	s_mov_b64 s[42:43], 0
	s_branch .LBB0_1118

.LBB0_1324:
	s_or_b64 exec, exec, s[36:37]
	v_cvt_f32_u32_e32 v5, v3
	s_waitcnt vmcnt(0)
	v_readfirstlane_b32 s19, v4
	v_sub_u32_e32 v4, 0, v3
	v_rcp_iflag_f32_e32 v5, v5
	v_add_u32_e32 v6, s19, v0
	v_mul_f32_e32 v5, 0x4f7ffffe, v5
	v_cvt_u32_f32_e32 v5, v5
	v_mul_lo_u32 v0, v4, v5
	v_mul_hi_u32 v0, v5, v0
	v_add_u32_e32 v0, v5, v0
	v_mul_hi_u32 v0, v6, v0
	v_mul_lo_u32 v4, v0, v3
	v_sub_u32_e32 v4, v6, v4
	v_add_u32_e32 v5, 1, v0
	v_cmp_ge_u32_e32 vcc, v4, v3
	s_nop 1
	v_cndmask_b32_e32 v0, v0, v5, vcc
	v_sub_u32_e32 v5, v4, v3
	v_cndmask_b32_e32 v4, v4, v5, vcc
	v_add_u32_e32 v5, 1, v0
	v_cmp_ge_u32_e32 vcc, v4, v3
	v_add_u32_e32 v4, 1, v6
	s_nop 0
	v_cndmask_b32_e32 v0, v0, v5, vcc
	v_mul_lo_u32 v5, v3, v0
	v_add_u32_e32 v3, v5, v3
	v_cmp_ne_u32_e32 vcc, v4, v3
	s_and_saveexec_b64 s[20:21], vcc
	s_xor_b64 s[36:37], exec, s[20:21]
	s_cbranch_execz .LBB0_1338
	v_readlane_b32 s12, v254, 50
	v_readlane_b32 s13, v254, 51
	s_waitcnt lgkmcnt(0)
	s_nop 3
	global_load_dword v2, v1, s[12:13] sc1
	s_waitcnt vmcnt(0)
	v_cmp_eq_u32_e32 vcc, v2, v0
	s_and_saveexec_b64 s[38:39], vcc
	s_cbranch_execz .LBB0_1337
	s_mov_b32 s19, 1
	s_mov_b64 s[40:41], 0
	s_branch .LBB0_1328
